# attention: output accumulators start from SrcC=0 in the first peeled iteration; 31 zero-fill moves per item removed
# baseline (speedup 1.0000x reference)
.LBB0_896:
	s_andn2_saveexec_b64 s[44:45], s[44:45]
	s_cbranch_execz .LBB0_876
	v_mov_b32_e32 v129, v250
	v_lshrrev_b32_e32 v168, 1, v250
	v_and_b32_e32 v168, 0xe0, v168
	v_and_b32_e32 v169, 31, v250
	v_or_b32_e32 v168, v168, v169
	v_mul_u32_u24_e32 v168, 0x1200, v168
	v_bfe_u32 v169, v250, 5, 1
	v_lshl_or_b32 v168, v169, 4, v168
	v_lshrrev_b32_e32 v169, 3, v250
	v_and_b32_e32 v171, 7, v250
	v_mul_u32_u24_e32 v170, 0x1200, v169
	v_lshl_or_b32 v170, v171, 4, v170
	s_lshl_b32 s18, s8, 1
	v_mul_lo_u32 v169, s18, v169
	v_lshl_or_b32 v169, v171, 4, v169
	v_lshrrev_b32_e32 v171, 6, v250
	v_lshlrev_b32_e32 v171, 10, v171
	v_and_b32_e32 v172, 63, v250
	v_lshlrev_b32_e32 v172, 4, v172
	v_lshrrev_b32_e32 v173, 6, v250
	v_lshl_or_b32 v172, v173, 10, v172
	v_add_u32_e32 v173, 0x10000, v172
	s_waitcnt lgkmcnt(0)
	s_barrier
	v_readlane_b32 s9, v254, 52
	v_lshlrev_b32_e32 v2, 4, v129
	v_lshlrev_b32_e32 v3, 1, v129
	v_lshrrev_b32_e32 v131, 1, v129
	v_lshlrev_b32_e32 v0, 3, v129
	v_xor_b32_e32 v4, v2, v129
	v_and_b32_e32 v2, 19, v129
	v_and_b32_e32 v3, 8, v3
	v_and_b32_e32 v5, 4, v131
	v_ashrrev_i32_e32 v128, 3, v129
	v_and_b32_e32 v130, 56, v0
	v_or3_b32 v5, v3, v2, v5
	v_mov_b64_e32 v[2:3], s[40:41]
	v_mad_i64_i32 v[0:1], s[2:3], v128, s21, 0
	v_lshlrev_b32_e32 v176, 1, v130
	v_mad_i64_i32 v[2:3], s[2:3], v128, s33, v[2:3]
	v_lshl_add_u64 v[132:133], v[2:3], 0, v[176:177]
	v_lshlrev_b32_e32 v2, 7, v128
	s_movk_i32 s2, 0x70
	v_and_or_b32 v142, v4, s2, v2
	s_mov_b32 s2, 0xd8000
	v_lshl_add_u64 v[0:1], v[0:1], 1, s[42:43]
	v_add_co_u32_e32 v2, vcc, s2, v132
	v_lshl_add_u64 v[0:1], v[0:1], 0, v[176:177]
	v_lshrrev_b32_e32 v40, 1, v5
	v_bfe_u32 v138, v129, 5, 1
	ds_read_b128 v[64:67], v173 offset:32768
	ds_read_b128 v[68:71], v173 offset:40960
	ds_read_b128 v[72:75], v173 offset:49152
	ds_read_b128 v[76:79], v173 offset:57344
	ds_read_b128 v[96:99], v173
	ds_read_b128 v[100:103], v173 offset:8192
	ds_read_b128 v[104:107], v173 offset:16384
	ds_read_b128 v[108:111], v173 offset:24576
	s_waitcnt lgkmcnt(4)
	ds_write_b128 v142, v[64:67] offset:16384
	ds_write_b128 v142, v[68:71] offset:24576
	ds_write_b128 v142, v[72:75]
	ds_write_b128 v142, v[76:79] offset:8192
	v_addc_co_u32_e32 v3, vcc, 0, v133, vcc
	global_load_dwordx4 v[112:115], v[2:3], off offset:2048
	global_load_dwordx4 v[116:119], v[0:1], off offset:128
	v_bitop3_b32 v0, v40, v138, 7 bitop3:0x6c
	v_lshlrev_b32_e32 v143, 7, v5
	v_lshlrev_b32_e32 v145, 4, v0
	s_waitcnt lgkmcnt(0)
	s_barrier
	v_or_b32_e32 v41, v143, v145
	ds_read_b128 v[0:3], v41 offset:16384
	ds_read_b128 v[4:7], v41 offset:20480
	s_waitcnt lgkmcnt(0)
	v_mfma_f32_32x32x16_bf16 v[16:31], v[0:3], v[96:99], 0
	v_or_b32_e32 v32, 2, v138
	v_bitop3_b32 v32, v40, v32, 7 bitop3:0x6c
	v_lshlrev_b32_e32 v146, 4, v32
	v_or_b32_e32 v42, v143, v146
	ds_read_b128 v[32:35], v42 offset:16384
	ds_read_b128 v[36:39], v42 offset:20480
	v_lshrrev_b32_e32 v73, 5, v129
	v_bfe_u32 v74, v129, 1, 3
	v_mfma_f32_32x32x16_bf16 v[0:15], v[4:7], v[96:99], 0
	s_lshr_b32 s2, s21, 6
	v_mad_i64_i32 v[134:135], s[18:19], v128, s33, 0
	s_add_i32 s2, s2, -1
	v_and_b32_e32 v148, 31, v129
	v_lshlrev_b32_e32 v75, 7, v148
	s_mov_b32 s3, 5
	s_waitcnt lgkmcnt(1)
	v_mfma_f32_32x32x16_bf16 v[16:31], v[32:35], v[100:103], v[16:31]
	v_or_b32_e32 v32, 4, v138
	v_bitop3_b32 v32, v40, v32, 7 bitop3:0x6c
	v_lshlrev_b32_e32 v147, 4, v32
	v_or_b32_e32 v43, v143, v147
	s_waitcnt lgkmcnt(0)
	v_mfma_f32_32x32x16_bf16 v[0:15], v[36:39], v[100:103], v[0:15]
	ds_read_b128 v[32:35], v43 offset:16384
	ds_read_b128 v[36:39], v43 offset:20480
	s_waitcnt lgkmcnt(1)
	v_mfma_f32_32x32x16_bf16 v[16:31], v[32:35], v[104:107], v[16:31]
	v_or_b32_e32 v32, 6, v138
	v_bitop3_b32 v32, v40, v32, 7 bitop3:0x6c
	v_lshlrev_b32_e32 v149, 4, v32
	v_or_b32_e32 v72, v143, v149
	ds_read_b128 v[32:35], v72 offset:16384
	s_waitcnt lgkmcnt(1)
	v_mfma_f32_32x32x16_bf16 v[0:15], v[36:39], v[104:107], v[0:15]
	ds_read_b128 v[36:39], v72 offset:20480
	s_waitcnt lgkmcnt(1)
	v_mfma_f32_32x32x16_bf16 v[16:31], v[32:35], v[108:111], v[16:31]
	s_waitcnt lgkmcnt(0)
	v_mfma_f32_32x32x16_bf16 v[0:15], v[36:39], v[108:111], v[0:15]
	s_nop 9
	v_exp_f32_e32 v32, v16
	v_exp_f32_e32 v33, v17
	v_exp_f32_e32 v34, v18
	v_exp_f32_e32 v35, v19
	v_exp_f32_e32 v37, v20
	v_exp_f32_e32 v38, v21
	v_add_f32_e32 v16, 0, v32
	v_add_f32_e32 v17, 0, v33
	v_add_f32_e32 v36, 0, v34
	v_add_f32_e32 v39, 0, v35
	v_add_f32_e32 v40, v37, v16
	v_add_f32_e32 v44, v38, v17
	v_exp_f32_e32 v45, v22
	v_exp_f32_e32 v46, v23
	ds_read_b128 v[16:19], v41 offset:24576
	ds_read_b128 v[20:23], v41 offset:28672
	s_waitcnt lgkmcnt(1)
	v_mfma_f32_32x32x16_bf16 v[48:63], v[16:19], v[96:99], 0
	v_exp_f32_e32 v41, v24
	v_add_f32_e32 v36, v45, v36
	v_add_f32_e32 v39, v46, v39
	ds_read_b128 v[64:67], v42 offset:24576
	ds_read_b128 v[68:71], v42 offset:28672
	v_exp_f32_e32 v42, v25
	v_add_f32_e32 v24, v41, v40
	v_exp_f32_e32 v40, v26
	v_exp_f32_e32 v47, v27
	v_exp_f32_e32 v28, v28
	v_exp_f32_e32 v29, v29
	v_exp_f32_e32 v30, v30
	v_exp_f32_e32 v31, v31
	v_exp_f32_e32 v77, v0
	v_exp_f32_e32 v78, v1
	v_add_f32_e32 v25, v42, v44
	s_waitcnt lgkmcnt(1)
	v_mfma_f32_32x32x16_bf16 v[48:63], v[64:67], v[100:103], v[48:63]
	v_add_f32_e32 v26, v40, v36
	v_add_f32_e32 v27, v47, v39
	v_cvt_pk_bf16_f32 v80, v32, v33
	v_cvt_pk_bf16_f32 v81, v34, v35
	v_cvt_pk_bf16_f32 v82, v37, v38
	v_cvt_pk_bf16_f32 v83, v45, v46
	v_add_f32_e32 v24, v28, v24
	v_add_f32_e32 v25, v29, v25
	v_exp_f32_e32 v4, v4
	v_add_f32_e32 v76, v30, v26
	v_add_f32_e32 v0, v31, v27
	v_add_f32_e32 v79, v77, v24
	v_add_f32_e32 v88, v78, v25
	ds_read_b128 v[16:19], v43 offset:24576
	ds_read_b128 v[24:27], v43 offset:28672
	v_cvt_pk_bf16_f32 v86, v28, v29
	v_exp_f32_e32 v28, v2
	v_exp_f32_e32 v29, v3
	v_exp_f32_e32 v5, v5
	s_waitcnt lgkmcnt(1)
	v_mfma_f32_32x32x16_bf16 v[48:63], v[16:19], v[104:107], v[48:63]
	v_cvt_pk_bf16_f32 v84, v41, v42
	v_cvt_pk_bf16_f32 v85, v40, v47
	v_exp_f32_e32 v6, v6
	v_exp_f32_e32 v7, v7
	v_cvt_pk_bf16_f32 v87, v30, v31
	v_add_f32_e32 v30, v28, v76
	v_add_f32_e32 v31, v29, v0
	v_mfma_f32_32x32x16_bf16 v[32:47], v[20:23], v[96:99], 0
	ds_read_b128 v[0:3], v72 offset:24576
	ds_read_b128 v[20:23], v72 offset:28672
	v_add_f32_e32 v64, v4, v79
	v_add_f32_e32 v65, v5, v88
	v_add_f32_e32 v30, v6, v30
	v_exp_f32_e32 v8, v8
	v_exp_f32_e32 v9, v9
	v_add_f32_e32 v31, v7, v31
	v_cvt_pk_bf16_f32 v90, v4, v5
	v_exp_f32_e32 v4, v10
	v_exp_f32_e32 v5, v11
	v_exp_f32_e32 v11, v13
	v_cvt_pk_bf16_f32 v91, v6, v7
	v_exp_f32_e32 v7, v12
	s_waitcnt lgkmcnt(1)
	v_mfma_f32_32x32x16_bf16 v[48:63], v[0:3], v[108:111], v[48:63]
	v_exp_f32_e32 v0, v14
	v_exp_f32_e32 v1, v15
	v_add_f32_e32 v64, v8, v64
	v_add_f32_e32 v65, v9, v65
	v_cvt_pk_bf16_f32 v88, v77, v78
	v_cvt_pk_bf16_f32 v89, v28, v29
	v_add_f32_e32 v6, v4, v30
	v_mfma_f32_32x32x16_bf16 v[32:47], v[68:71], v[100:103], v[32:47]
	v_add_f32_e32 v10, v5, v31
	v_mov_b32_e32 v16, 0
	v_add_f32_e32 v12, v7, v64
	v_add_f32_e32 v2, v11, v65
	v_add_f32_e32 v3, v0, v6
	v_add_f32_e32 v6, v1, v10
	v_mfma_f32_32x32x16_bf16 v[32:47], v[24:27], v[104:107], v[32:47]
	v_cvt_pk_bf16_f32 v95, v0, v1
	v_add_f32_e32 v0, v12, v2
	v_add_f32_e32 v1, v3, v6
	v_add_f32_e32 v0, v0, v1
	v_add_f32_e32 v150, 0, v0
	v_bitop3_b32 v0, v73, v74, 1 bitop3:0x6c
	v_lshlrev_b32_e32 v2, 4, v0
	v_bitop3_b32 v0, v138, v74, 2 bitop3:0x36
	v_lshlrev_b32_e32 v3, 4, v0
	v_bitop3_b32 v0, v138, v74, 4 bitop3:0x36
	v_cvt_pk_bf16_f32 v93, v4, v5
	v_lshlrev_b32_e32 v4, 4, v0
	v_bitop3_b32 v0, v138, v74, 6 bitop3:0x36
	v_lshlrev_b32_e32 v5, 4, v0
	v_and_b32_e32 v0, 7, v129
	v_cvt_pk_bf16_f32 v92, v8, v9
	v_cvt_pk_bf16_f32 v94, v7, v11
	v_lshlrev_b32_e32 v176, 4, v0
	v_lshlrev_b32_e32 v0, 1, v128
	s_waitcnt lgkmcnt(0)
	s_barrier
	v_mad_i64_i32 v[0:1], s[18:19], v0, s21, v[176:177]
	s_add_u32 s18, s9, s38
	v_readlane_b32 s9, v254, 53
	s_addc_u32 s19, s9, s39
	s_waitcnt lgkmcnt(0)
	v_mfma_f32_32x32x16_bf16 v[32:47], v[20:23], v[108:111], v[32:47]
	v_lshl_add_u64 v[136:137], s[18:19], 0, v[0:1]
	v_add_u32_e32 v144, v75, v2
	v_add_u32_e32 v141, v75, v3
	v_add_u32_e32 v140, v75, v4
	v_add_u32_e32 v139, v75, v5
	v_add_u32_e32 v164, v143, v145
	v_add_u32_e32 v165, v143, v146
	v_add_u32_e32 v166, v143, v147
	v_add_u32_e32 v167, v143, v149
.Lpeel_0:
	s_add_i32 s9, s3, -1
	s_min_u32 s9, s9, s2
	s_lshl_b32 s9, s9, 6
	s_waitcnt vmcnt(1)
	ds_write_b128 v142, v[112:115] offset:16384
	s_waitcnt vmcnt(0)
	ds_write_b128 v142, v[116:119] offset:24576
	v_mad_u64_u32 v[64:65], s[18:19], s9, v237, v[132:133]
	global_load_dwordx4 v[120:123], v[64:65], off offset:2048
	global_load_dwordx4 v[124:127], v[136:137], off offset:-128
	ds_read_b128 v[64:67], v144 offset:8192
	ds_read_b128 v[68:71], v144 offset:12288
	ds_read_b128 v[72:75], v141 offset:8192
	ds_read_b128 v[76:79], v141 offset:12288
	v_exp_f32_e32 v151, v48
	v_exp_f32_e32 v152, v49
	s_waitcnt lgkmcnt(3)
	v_mfma_f32_32x32x16_bf16 v[16:31], v[64:67], v[80:83], 0
	v_exp_f32_e32 v153, v50
	v_exp_f32_e32 v154, v51
	ds_read_b128 v[48:51], v140 offset:8192
	ds_read_b128 v[64:67], v140 offset:12288
	v_exp_f32_e32 v155, v52
	s_waitcnt lgkmcnt(4)
	v_mfma_f32_32x32x16_bf16 v[0:15], v[68:71], v[80:83], 0
	v_exp_f32_e32 v156, v53
	v_exp_f32_e32 v159, v54
	v_exp_f32_e32 v160, v55
	v_exp_f32_e32 v162, v57
	s_waitcnt lgkmcnt(3)
	v_mfma_f32_32x32x16_bf16 v[16:31], v[72:75], v[84:87], v[16:31]
	ds_read_b128 v[68:71], v139 offset:8192
	ds_read_b128 v[80:83], v139 offset:12288
	v_add_f32_e32 v157, v155, v151
	v_add_f32_e32 v158, v156, v152
	ds_read_b128 v[52:55], v164
	ds_read_b128 v[72:75], v164 offset:4096
	v_add_f32_e32 v161, v159, v153
	s_waitcnt lgkmcnt(6)
	v_mfma_f32_32x32x16_bf16 v[0:15], v[76:79], v[84:87], v[0:15]
	v_exp_f32_e32 v77, v56
	v_add_f32_e32 v76, v160, v154
	v_exp_f32_e32 v62, v62
	ds_read_b128 v[112:115], v165
	ds_read_b128 v[116:119], v165 offset:4096
	v_cvt_pk_bf16_f32 v56, v151, v152
	s_waitcnt lgkmcnt(7)
	v_mfma_f32_32x32x16_bf16 v[16:31], v[48:51], v[88:91], v[16:31]
	v_exp_f32_e32 v49, v58
	v_exp_f32_e32 v50, v59
	v_add_f32_e32 v48, v77, v157
	v_add_f32_e32 v51, v162, v158
	v_add_f32_e32 v78, v49, v161
	v_add_f32_e32 v76, v50, v76
	s_waitcnt lgkmcnt(6)
	v_mfma_f32_32x32x16_bf16 v[0:15], v[64:67], v[88:91], v[0:15]
	v_exp_f32_e32 v60, v60
	v_add_f32_e32 v151, v62, v78
	v_exp_f32_e32 v61, v61
	v_exp_f32_e32 v63, v63
	v_cvt_pk_bf16_f32 v59, v159, v160
	v_exp_f32_e32 v160, v33
	s_waitcnt lgkmcnt(5)
	v_mfma_f32_32x32x16_bf16 v[16:31], v[68:71], v[92:95], v[16:31]
	v_cvt_pk_bf16_f32 v57, v153, v154
	v_cvt_pk_bf16_f32 v58, v155, v156
	v_add_f32_e32 v48, v60, v48
	v_add_f32_e32 v51, v61, v51
	v_cvt_pk_bf16_f32 v49, v49, v50
	s_waitcnt lgkmcnt(4)
	v_mfma_f32_32x32x16_bf16 v[0:15], v[80:83], v[92:95], v[0:15]
	v_readfirstlane_b32 s18, v171
	s_add_u32 m0, s18, 0x7600
	s_nop 0
	global_load_lds_dwordx4 v168, s[12:13] offset:2560
	v_exp_f32_e32 v95, v32
	v_add_f32_e32 v32, v63, v76
	v_add_f32_e32 v163, v160, v51
	v_add_f32_e32 v161, v95, v48
	v_cvt_pk_bf16_f32 v48, v77, v162
	v_cvt_pk_bf16_f32 v51, v62, v63
	s_waitcnt lgkmcnt(3)
	v_mfma_f32_32x32x16_bf16 v[78:93], v[52:55], v[96:99], 0
	v_cvt_pk_bf16_f32 v50, v60, v61
	v_exp_f32_e32 v60, v34
	v_exp_f32_e32 v61, v35
	v_exp_f32_e32 v36, v36
	v_exp_f32_e32 v37, v37
	v_exp_f32_e32 v38, v38
	v_exp_f32_e32 v39, v39
	s_waitcnt lgkmcnt(2)
	v_mfma_f32_32x32x16_bf16 v[62:77], v[72:75], v[96:99], 0
	ds_read_b128 v[52:55], v166
	ds_read_b128 v[152:155], v166 offset:4096
	v_add_f32_e32 v151, v60, v151
	v_add_f32_e32 v162, v61, v32
	s_waitcnt lgkmcnt(3)
	v_mfma_f32_32x32x16_bf16 v[78:93], v[112:115], v[100:103], v[78:93]
	v_add_f32_e32 v112, v36, v161
	v_add_f32_e32 v113, v37, v163
	v_add_f32_e32 v114, v38, v151
	v_exp_f32_e32 v115, v40
	v_add_f32_e32 v40, v39, v162
	ds_read_b128 v[32:35], v167
	ds_read_b128 v[156:159], v167 offset:4096
	s_waitcnt lgkmcnt(4)
	v_mfma_f32_32x32x16_bf16 v[62:77], v[116:119], v[100:103], v[62:77]
	v_exp_f32_e32 v116, v41
	v_add_f32_e32 v41, v115, v112
	s_min_u32 s9, s3, s2
	s_lshl_b32 s9, s9, 6
	v_add_f32_e32 v112, v116, v113
	s_waitcnt lgkmcnt(3)
	v_mfma_f32_32x32x16_bf16 v[78:93], v[52:55], v[104:107], v[78:93]
	v_cvt_pk_bf16_f32 v54, v36, v37
	v_exp_f32_e32 v37, v42
	v_cvt_pk_bf16_f32 v55, v38, v39
	v_exp_f32_e32 v38, v43
	v_exp_f32_e32 v39, v44
	v_exp_f32_e32 v44, v45
	v_exp_f32_e32 v45, v46
	v_exp_f32_e32 v46, v47
	v_cvt_pk_bf16_f32 v52, v95, v160
	v_cvt_pk_bf16_f32 v53, v60, v61
	v_add_f32_e32 v36, v37, v114
	v_add_f32_e32 v43, v38, v40
	v_add_f32_e32 v40, v39, v41
	v_add_f32_e32 v42, v44, v112
	v_add_f32_e32 v41, v45, v36
	v_add_f32_e32 v43, v46, v43
	v_cvt_pk_bf16_f32 v36, v115, v116
	v_cvt_pk_bf16_f32 v37, v37, v38
	v_cvt_pk_bf16_f32 v38, v39, v44
	v_cvt_pk_bf16_f32 v39, v45, v46
	s_waitcnt lgkmcnt(1)
	v_mfma_f32_32x32x16_bf16 v[78:93], v[32:35], v[108:111], v[78:93]
	s_waitcnt lgkmcnt(0)
	s_barrier
	v_mad_u64_u32 v[32:33], s[18:19], s9, v237, v[132:133]
	global_load_dwordx4 v[112:115], v[32:33], off offset:2048
	global_load_dwordx4 v[116:119], v[136:137], off
	v_add_f32_e64 v32, v40, v42
	v_add_f32_e64 v33, v41, v43
	s_waitcnt vmcnt(4)
	ds_write_b128 v142, v[120:123]
	s_waitcnt vmcnt(3)
	ds_write_b128 v142, v[124:127] offset:8192
	v_mfma_f32_32x32x16_bf16 v[62:77], v[152:155], v[104:107], v[62:77]
	v_add_f32_e32 v32, v32, v33
	v_add_f32_e32 v150, v150, v32
	s_waitcnt lgkmcnt(2)
	v_mfma_f32_32x32x16_bf16 v[62:77], v[156:159], v[108:111], v[62:77]
	ds_read_b128 v[32:35], v144 offset:24576
	ds_read_b128 v[40:43], v144 offset:28672
	ds_read_b128 v[44:47], v141 offset:24576
	ds_read_b128 v[120:123], v141 offset:28672
	v_exp_f32_e32 v60, v78
	s_waitcnt lgkmcnt(3)
	v_mfma_f32_32x32x16_bf16 v[16:31], v[32:35], v[56:59], v[16:31]
	v_exp_f32_e32 v61, v79
	v_exp_f32_e32 v95, v80
	v_exp_f32_e32 v81, v81
	ds_read_b128 v[152:155], v140 offset:24576
	ds_read_b128 v[156:159], v140 offset:28672
	s_waitcnt lgkmcnt(4)
	v_mfma_f32_32x32x16_bf16 v[0:15], v[40:43], v[56:59], v[0:15]
	v_exp_f32_e32 v82, v82
	v_exp_f32_e32 v83, v83
	v_add_f32_e32 v78, v82, v60
	v_add_f32_e32 v79, v83, v61
	s_waitcnt lgkmcnt(2)
	v_mfma_f32_32x32x16_bf16 v[0:15], v[120:123], v[48:51], v[0:15]
	ds_read_b128 v[56:59], v139 offset:24576
	ds_read_b128 v[160:163], v139 offset:28672
	ds_read_b128 v[40:43], v164 offset:16384
	ds_read_b128 v[32:35], v164 offset:20480
	v_cvt_pk_bf16_f32 v82, v82, v83
	v_exp_f32_e32 v151, v62
	v_exp_f32_e32 v64, v64
	v_exp_f32_e32 v65, v65
	v_mfma_f32_32x32x16_bf16 v[16:31], v[44:47], v[48:51], v[16:31]
	v_exp_f32_e32 v44, v84
	v_exp_f32_e32 v45, v85
	v_exp_f32_e32 v84, v86
	v_exp_f32_e32 v85, v87
	v_add_f32_e32 v46, v44, v95
	v_add_f32_e32 v47, v45, v81
	v_add_f32_e32 v48, v84, v78
	s_waitcnt lgkmcnt(4)
	v_mfma_f32_32x32x16_bf16 v[0:15], v[156:159], v[52:55], v[0:15]
	v_add_f32_e32 v49, v85, v79
	v_exp_f32_e32 v78, v88
	v_exp_f32_e32 v79, v89
	v_exp_f32_e32 v87, v92
	v_cvt_pk_bf16_f32 v83, v44, v45
	v_exp_f32_e32 v44, v90
	v_mfma_f32_32x32x16_bf16 v[16:31], v[152:155], v[52:55], v[16:31]
	v_exp_f32_e32 v45, v91
	v_exp_f32_e32 v92, v93
	v_add_f32_e32 v46, v78, v46
	v_add_f32_e32 v47, v79, v47
	ds_read_b128 v[124:127], v165 offset:16384
	ds_read_b128 v[120:123], v165 offset:20480
	s_waitcnt lgkmcnt(4)
	v_mfma_f32_32x32x16_bf16 v[0:15], v[160:163], v[36:39], v[0:15]
	v_exp_f32_e32 v160, v63
	v_cvt_pk_bf16_f32 v80, v60, v61
	v_cvt_pk_bf16_f32 v81, v95, v81
	v_add_f32_e32 v48, v44, v48
	v_add_f32_e32 v49, v45, v49
	v_add_f32_e32 v46, v87, v46
	v_add_f32_e32 v47, v92, v47
	v_mfma_f32_32x32x16_bf16 v[16:31], v[56:59], v[36:39], v[16:31]
	v_add_f32_e32 v161, v151, v48
	v_add_f32_e32 v162, v160, v49
	v_cvt_pk_bf16_f32 v84, v84, v85
	v_cvt_pk_bf16_f32 v85, v78, v79
	v_cvt_pk_bf16_f32 v86, v44, v45
	v_add_f32_e32 v78, v64, v46
	v_add_f32_e32 v79, v65, v47
	s_waitcnt lgkmcnt(3)
	v_mfma_f32_32x32x16_bf16 v[48:63], v[40:43], v[96:99], 0
	ds_read_b128 v[88:91], v166 offset:16384
	ds_read_b128 v[152:155], v166 offset:20480
	v_exp_f32_e32 v66, v66
	v_exp_f32_e32 v67, v67
	v_exp_f32_e32 v68, v68
	v_exp_f32_e32 v69, v69
	v_cvt_pk_bf16_f32 v87, v87, v92
	s_waitcnt lgkmcnt(4)
	v_mfma_f32_32x32x16_bf16 v[32:47], v[32:35], v[96:99], 0
	ds_read_b128 v[156:159], v167 offset:16384
	ds_read_b128 v[92:95], v167 offset:20480
	v_add_f32_e32 v161, v66, v161
	v_add_f32_e32 v162, v67, v162
	v_add_f32_e32 v78, v68, v78
	v_add_f32_e32 v79, v69, v79
	s_waitcnt lgkmcnt(5)
	v_mfma_f32_32x32x16_bf16 v[48:63], v[124:127], v[100:103], v[48:63]
	v_exp_f32_e32 v70, v70
	v_exp_f32_e32 v71, v71
	s_add_i32 s9, s3, 2
	s_add_i32 s3, s3, -2
	v_lshl_add_u64 v[136:137], v[136:137], 0, s[22:23]
	s_waitcnt lgkmcnt(4)
	v_mfma_f32_32x32x16_bf16 v[32:47], v[120:123], v[100:103], v[32:47]
	v_add_f32_e32 v120, v70, v161
	v_add_f32_e32 v121, v71, v162
	s_cmp_lt_u32 s3, s2
	s_mov_b32 s3, s9
	s_waitcnt lgkmcnt(3)
	v_mfma_f32_32x32x16_bf16 v[48:63], v[88:91], v[104:107], v[48:63]
	v_cvt_pk_bf16_f32 v91, v68, v69
	v_exp_f32_e32 v68, v72
	v_exp_f32_e32 v69, v73
	v_exp_f32_e32 v72, v74
	v_exp_f32_e32 v73, v75
	v_exp_f32_e32 v74, v76
	v_exp_f32_e32 v75, v77
	s_waitcnt lgkmcnt(2)
	v_mfma_f32_32x32x16_bf16 v[32:47], v[152:155], v[104:107], v[32:47]
	v_cvt_pk_bf16_f32 v88, v151, v160
	v_cvt_pk_bf16_f32 v89, v64, v65
	v_cvt_pk_bf16_f32 v90, v66, v67
	v_add_f32_e32 v65, v68, v78
	v_add_f32_e32 v67, v69, v79
	s_waitcnt lgkmcnt(1)
	v_mfma_f32_32x32x16_bf16 v[48:63], v[156:159], v[108:111], v[48:63]
	v_add_f32_e32 v64, v72, v120
	v_add_f32_e32 v66, v73, v121
	v_add_f32_e32 v65, v74, v65
	v_add_f32_e32 v67, v75, v67
	s_waitcnt lgkmcnt(0)
	v_mfma_f32_32x32x16_bf16 v[32:47], v[92:95], v[108:111], v[32:47]
	v_cvt_pk_bf16_f32 v92, v70, v71
	v_cvt_pk_bf16_f32 v93, v68, v69
	v_cvt_pk_bf16_f32 v94, v72, v73
	v_cvt_pk_bf16_f32 v95, v74, v75
	v_add_f32_e64 v64, v64, v66
	v_add_f32_e64 v65, v65, v67
	s_waitcnt lgkmcnt(0)
	s_barrier
	v_add_f32_e32 v64, v64, v65
	v_add_f32_e32 v150, v150, v64
